# added: the six GEMM K-loop heads aligned to 64-byte boundaries
# speedup vs baseline: 1.0096x; 1.0096x over previous
.LBB0_213:
	s_ashr_i32 s45, s44, 31
	s_lshl_b64 s[2:3], s[44:45], 19
	s_add_u32 s46, s18, s2
	s_addc_u32 s47, s19, s3
	s_and_b64 s[2:3], s[38:39], exec
	s_cselect_b32 s2, s47, s53
	s_cselect_b32 s3, s46, s52
	s_ashr_i32 s43, s42, 31
	s_lshl_b64 s[24:25], s[42:43], 19
	s_add_u32 s48, s97, s24
	v_readlane_b32 s13, v255, 8
	s_addc_u32 s49, s13, s25
	s_and_b64 s[24:25], s[38:39], exec
	s_cselect_b32 s13, s49, s71
	s_cselect_b32 s16, s48, s70
	s_add_u32 s30, s52, 0x40080
	s_addc_u32 s31, s53, 0
	s_add_u32 s24, s70, 0x100
	s_addc_u32 s25, s71, 0
	s_mov_b32 s26, -2
	v_mov_b64_e32 v[2:3], 0
	v_mov_b64_e32 v[4:5], 0
	v_mov_b64_e32 v[6:7], 0
	v_mov_b64_e32 v[8:9], 0
	v_mov_b64_e32 v[10:11], 0
	v_mov_b64_e32 v[12:13], 0
	v_mov_b64_e32 v[14:15], 0
	v_mov_b64_e32 v[16:17], 0
	v_mov_b64_e32 v[18:19], 0
	v_mov_b64_e32 v[20:21], 0
	v_mov_b64_e32 v[22:23], 0
	v_mov_b64_e32 v[24:25], 0
	v_mov_b64_e32 v[26:27], 0
	v_mov_b64_e32 v[28:29], 0
	v_mov_b64_e32 v[30:31], 0
	v_mov_b64_e32 v[32:33], 0
	v_mov_b64_e32 v[34:35], 0
	v_mov_b64_e32 v[36:37], 0
	v_mov_b64_e32 v[38:39], 0
	v_mov_b64_e32 v[40:41], 0
	v_mov_b64_e32 v[42:43], 0
	v_mov_b64_e32 v[44:45], 0
	v_mov_b64_e32 v[46:47], 0
	v_mov_b64_e32 v[48:49], 0
	v_mov_b64_e32 v[50:51], 0
	v_mov_b64_e32 v[52:53], 0
	v_mov_b64_e32 v[54:55], 0
	v_mov_b64_e32 v[56:57], 0
	v_mov_b64_e32 v[58:59], 0
	v_mov_b64_e32 v[60:61], 0
	v_mov_b64_e32 v[62:63], 0
	v_mov_b64_e32 v[64:65], 0
	v_mov_b64_e32 v[66:67], 0
	v_mov_b64_e32 v[68:69], 0
	v_mov_b64_e32 v[70:71], 0
	v_mov_b64_e32 v[72:73], 0
	v_mov_b64_e32 v[74:75], 0
	v_mov_b64_e32 v[76:77], 0
	v_mov_b64_e32 v[78:79], 0
	v_mov_b64_e32 v[80:81], 0
	v_mov_b64_e32 v[82:83], 0
	v_mov_b64_e32 v[84:85], 0
	v_mov_b64_e32 v[86:87], 0
	v_mov_b64_e32 v[88:89], 0
	v_mov_b64_e32 v[90:91], 0
	v_mov_b64_e32 v[92:93], 0
	v_mov_b64_e32 v[94:95], 0
	v_mov_b64_e32 v[96:97], 0
	v_mov_b64_e32 v[98:99], 0
	v_mov_b64_e32 v[100:101], 0
	v_mov_b64_e32 v[102:103], 0
	v_mov_b64_e32 v[104:105], 0
	v_mov_b64_e32 v[106:107], 0
	v_mov_b64_e32 v[108:109], 0
	v_mov_b64_e32 v[110:111], 0
	v_mov_b64_e32 v[112:113], 0
	v_mov_b64_e32 v[114:115], 0
	v_mov_b64_e32 v[116:117], 0
	v_mov_b64_e32 v[118:119], 0
	v_mov_b64_e32 v[120:121], 0
	v_mov_b64_e32 v[122:123], 0
	v_mov_b64_e32 v[124:125], 0
	v_mov_b64_e32 v[126:127], 0
	v_mov_b64_e32 v[128:129], 0
	.p2align 6

.LBB0_694:
	s_ashr_i32 s45, s44, 31
	s_lshl_b64 s[24:25], s[44:45], 19
	s_add_u32 s46, s17, s24
	s_addc_u32 s47, s18, s25
	s_and_b64 s[24:25], s[42:43], exec
	s_cselect_b32 s3, s47, s13
	s_cselect_b32 s16, s46, s12
	s_ashr_i32 s35, s34, 31
	s_lshl_b64 s[24:25], s[34:35], 19
	s_add_u32 s48, s19, s24
	s_addc_u32 s49, s29, s25
	s_and_b64 s[24:25], s[42:43], exec
	s_cselect_b32 s24, s49, s31
	s_cselect_b32 s25, s48, s30
	s_add_u32 s12, s12, 0x40080
	s_addc_u32 s13, s13, 0
	s_add_u32 s26, s30, 0x100
	s_addc_u32 s28, s31, 0
	s_mov_b32 s35, -2
	s_waitcnt vmcnt(0)
	v_mov_b64_e32 v[2:3], 0
	v_mov_b64_e32 v[4:5], 0
	v_mov_b64_e32 v[6:7], 0
	v_mov_b64_e32 v[8:9], 0
	v_mov_b64_e32 v[10:11], 0
	v_mov_b64_e32 v[12:13], 0
	v_mov_b64_e32 v[14:15], 0
	v_mov_b64_e32 v[16:17], 0
	v_mov_b64_e32 v[18:19], 0
	v_mov_b64_e32 v[20:21], 0
	v_mov_b64_e32 v[22:23], 0
	v_mov_b64_e32 v[24:25], 0
	v_mov_b64_e32 v[26:27], 0
	v_mov_b64_e32 v[28:29], 0
	v_mov_b64_e32 v[30:31], 0
	v_mov_b64_e32 v[32:33], 0
	v_mov_b64_e32 v[34:35], 0
	v_mov_b64_e32 v[36:37], 0
	v_mov_b64_e32 v[38:39], 0
	v_mov_b64_e32 v[40:41], 0
	v_mov_b64_e32 v[42:43], 0
	v_mov_b64_e32 v[44:45], 0
	v_mov_b64_e32 v[46:47], 0
	v_mov_b64_e32 v[48:49], 0
	v_mov_b64_e32 v[50:51], 0
	v_mov_b64_e32 v[52:53], 0
	v_mov_b64_e32 v[54:55], 0
	v_mov_b64_e32 v[56:57], 0
	v_mov_b64_e32 v[58:59], 0
	v_mov_b64_e32 v[60:61], 0
	v_mov_b64_e32 v[62:63], 0
	v_mov_b64_e32 v[64:65], 0
	v_mov_b64_e32 v[66:67], 0
	v_mov_b64_e32 v[68:69], 0
	v_mov_b64_e32 v[70:71], 0
	v_mov_b64_e32 v[72:73], 0
	v_mov_b64_e32 v[74:75], 0
	v_mov_b64_e32 v[76:77], 0
	v_mov_b64_e32 v[78:79], 0
	v_mov_b64_e32 v[80:81], 0
	v_mov_b64_e32 v[82:83], 0
	v_mov_b64_e32 v[84:85], 0
	v_mov_b64_e32 v[86:87], 0
	v_mov_b64_e32 v[88:89], 0
	v_mov_b64_e32 v[90:91], 0
	v_mov_b64_e32 v[92:93], 0
	v_mov_b64_e32 v[94:95], 0
	v_mov_b64_e32 v[96:97], 0
	v_mov_b64_e32 v[98:99], 0
	v_mov_b64_e32 v[100:101], 0
	v_mov_b64_e32 v[102:103], 0
	v_mov_b64_e32 v[104:105], 0
	v_mov_b64_e32 v[106:107], 0
	v_mov_b64_e32 v[108:109], 0
	v_mov_b64_e32 v[110:111], 0
	v_mov_b64_e32 v[112:113], 0
	v_mov_b64_e32 v[114:115], 0
	v_mov_b64_e32 v[116:117], 0
	v_mov_b64_e32 v[118:119], 0
	v_mov_b64_e32 v[120:121], 0
	v_mov_b64_e32 v[122:123], 0
	v_mov_b64_e32 v[124:125], 0
	v_mov_b64_e32 v[126:127], 0
	v_mov_b64_e32 v[128:129], 0
	.p2align 6

.LBB0_791:
	s_ashr_i32 s15, s14, 31
	s_lshl_b64 s[20:21], s[14:15], 19
	s_add_u32 s20, s2, s20
	s_addc_u32 s21, s3, s21
	s_and_b64 s[30:31], s[4:5], exec
	s_cselect_b32 s15, s21, s35
	s_cselect_b32 s46, s20, s34
	s_ashr_i32 s13, s12, 31
	s_lshl_b64 s[30:31], s[12:13], 19
	s_add_u32 s30, s16, s30
	s_addc_u32 s31, s17, s31
	s_and_b64 s[40:41], s[4:5], exec
	s_cselect_b32 s13, s31, s37
	s_cselect_b32 s47, s30, s36
	s_add_u32 s34, s34, 0x40080
	s_addc_u32 s35, s35, 0
	s_add_u32 s48, s36, 0x100
	s_addc_u32 s49, s37, 0
	s_mov_b32 s50, -2
	v_mov_b64_e32 v[2:3], 0
	v_mov_b64_e32 v[4:5], 0
	v_mov_b64_e32 v[6:7], 0
	v_mov_b64_e32 v[8:9], 0
	v_mov_b64_e32 v[10:11], 0
	v_mov_b64_e32 v[12:13], 0
	v_mov_b64_e32 v[14:15], 0
	v_mov_b64_e32 v[16:17], 0
	v_mov_b64_e32 v[18:19], 0
	v_mov_b64_e32 v[20:21], 0
	v_mov_b64_e32 v[22:23], 0
	v_mov_b64_e32 v[24:25], 0
	v_mov_b64_e32 v[26:27], 0
	v_mov_b64_e32 v[28:29], 0
	v_mov_b64_e32 v[30:31], 0
	v_mov_b64_e32 v[32:33], 0
	v_mov_b64_e32 v[34:35], 0
	v_mov_b64_e32 v[36:37], 0
	v_mov_b64_e32 v[38:39], 0
	v_mov_b64_e32 v[40:41], 0
	v_mov_b64_e32 v[42:43], 0
	v_mov_b64_e32 v[44:45], 0
	v_mov_b64_e32 v[46:47], 0
	v_mov_b64_e32 v[48:49], 0
	v_mov_b64_e32 v[50:51], 0
	v_mov_b64_e32 v[52:53], 0
	v_mov_b64_e32 v[54:55], 0
	v_mov_b64_e32 v[56:57], 0
	v_mov_b64_e32 v[58:59], 0
	v_mov_b64_e32 v[60:61], 0
	v_mov_b64_e32 v[62:63], 0
	v_mov_b64_e32 v[64:65], 0
	v_mov_b64_e32 v[66:67], 0
	v_mov_b64_e32 v[68:69], 0
	v_mov_b64_e32 v[70:71], 0
	v_mov_b64_e32 v[72:73], 0
	v_mov_b64_e32 v[74:75], 0
	v_mov_b64_e32 v[76:77], 0
	v_mov_b64_e32 v[78:79], 0
	v_mov_b64_e32 v[80:81], 0
	v_mov_b64_e32 v[82:83], 0
	v_mov_b64_e32 v[84:85], 0
	v_mov_b64_e32 v[86:87], 0
	v_mov_b64_e32 v[88:89], 0
	v_mov_b64_e32 v[90:91], 0
	v_mov_b64_e32 v[92:93], 0
	v_mov_b64_e32 v[94:95], 0
	v_mov_b64_e32 v[96:97], 0
	v_mov_b64_e32 v[98:99], 0
	v_mov_b64_e32 v[100:101], 0
	v_mov_b64_e32 v[102:103], 0
	v_mov_b64_e32 v[104:105], 0
	v_mov_b64_e32 v[106:107], 0
	v_mov_b64_e32 v[108:109], 0
	v_mov_b64_e32 v[110:111], 0
	v_mov_b64_e32 v[112:113], 0
	v_mov_b64_e32 v[114:115], 0
	v_mov_b64_e32 v[116:117], 0
	v_mov_b64_e32 v[118:119], 0
	v_mov_b64_e32 v[120:121], 0
	v_mov_b64_e32 v[122:123], 0
	v_mov_b64_e32 v[124:125], 0
	v_mov_b64_e32 v[126:127], 0
	v_mov_b64_e32 v[128:129], 0
	.p2align 6

.LBB0_863:
	s_ashr_i32 s45, s44, 31
	s_lshl_b64 s[24:25], s[44:45], 21
	s_add_u32 s46, s17, s24
	s_addc_u32 s47, s18, s25
	s_and_b64 s[24:25], s[42:43], exec
	s_cselect_b32 s3, s47, s13
	s_cselect_b32 s16, s46, s12
	s_ashr_i32 s35, s34, 31
	s_lshl_b64 s[24:25], s[34:35], 21
	s_add_u32 s48, s19, s24
	s_addc_u32 s49, s29, s25
	s_and_b64 s[24:25], s[42:43], exec
	s_cselect_b32 s24, s49, s31
	s_cselect_b32 s25, s48, s30
	s_add_u32 s12, s12, 0x100080
	s_addc_u32 s13, s13, 0
	s_add_u32 s26, s30, 0x100
	s_addc_u32 s28, s31, 0
	s_mov_b32 s35, -2
	v_mov_b64_e32 v[2:3], 0
	v_mov_b64_e32 v[4:5], 0
	v_mov_b64_e32 v[6:7], 0
	v_mov_b64_e32 v[8:9], 0
	v_mov_b64_e32 v[10:11], 0
	v_mov_b64_e32 v[12:13], 0
	v_mov_b64_e32 v[14:15], 0
	v_mov_b64_e32 v[16:17], 0
	v_mov_b64_e32 v[18:19], 0
	v_mov_b64_e32 v[20:21], 0
	v_mov_b64_e32 v[22:23], 0
	v_mov_b64_e32 v[24:25], 0
	v_mov_b64_e32 v[26:27], 0
	v_mov_b64_e32 v[28:29], 0
	v_mov_b64_e32 v[30:31], 0
	v_mov_b64_e32 v[32:33], 0
	v_mov_b64_e32 v[34:35], 0
	v_mov_b64_e32 v[36:37], 0
	v_mov_b64_e32 v[38:39], 0
	v_mov_b64_e32 v[40:41], 0
	v_mov_b64_e32 v[42:43], 0
	v_mov_b64_e32 v[44:45], 0
	v_mov_b64_e32 v[46:47], 0
	v_mov_b64_e32 v[48:49], 0
	v_mov_b64_e32 v[50:51], 0
	v_mov_b64_e32 v[52:53], 0
	v_mov_b64_e32 v[54:55], 0
	v_mov_b64_e32 v[56:57], 0
	v_mov_b64_e32 v[58:59], 0
	v_mov_b64_e32 v[60:61], 0
	v_mov_b64_e32 v[62:63], 0
	v_mov_b64_e32 v[64:65], 0
	v_mov_b64_e32 v[66:67], 0
	v_mov_b64_e32 v[68:69], 0
	v_mov_b64_e32 v[70:71], 0
	v_mov_b64_e32 v[72:73], 0
	v_mov_b64_e32 v[74:75], 0
	v_mov_b64_e32 v[76:77], 0
	v_mov_b64_e32 v[78:79], 0
	v_mov_b64_e32 v[80:81], 0
	v_mov_b64_e32 v[82:83], 0
	v_mov_b64_e32 v[84:85], 0
	v_mov_b64_e32 v[86:87], 0
	v_mov_b64_e32 v[88:89], 0
	v_mov_b64_e32 v[90:91], 0
	v_mov_b64_e32 v[92:93], 0
	v_mov_b64_e32 v[94:95], 0
	v_mov_b64_e32 v[96:97], 0
	v_mov_b64_e32 v[98:99], 0
	v_mov_b64_e32 v[100:101], 0
	v_mov_b64_e32 v[102:103], 0
	v_mov_b64_e32 v[104:105], 0
	v_mov_b64_e32 v[106:107], 0
	v_mov_b64_e32 v[108:109], 0
	v_mov_b64_e32 v[110:111], 0
	v_mov_b64_e32 v[112:113], 0
	v_mov_b64_e32 v[114:115], 0
	v_mov_b64_e32 v[116:117], 0
	v_mov_b64_e32 v[118:119], 0
	v_mov_b64_e32 v[120:121], 0
	v_mov_b64_e32 v[122:123], 0
	v_mov_b64_e32 v[124:125], 0
	v_mov_b64_e32 v[126:127], 0
	v_mov_b64_e32 v[128:129], 0
	.p2align 6

.LBB0_955:
	v_mov_b32_e32 v125, 0
	s_andn2_b64 vcc, exec, s[20:21]
	v_mov_b32_e32 v124, v125
	v_mov_b32_e32 v123, v125
	v_mov_b32_e32 v122, v125
	v_mov_b32_e32 v129, v125
	v_mov_b32_e32 v128, v125
	v_mov_b32_e32 v127, v125
	v_mov_b32_e32 v126, v125
	v_mov_b32_e32 v113, v125
	v_mov_b32_e32 v112, v125
	v_mov_b32_e32 v111, v125
	v_mov_b32_e32 v110, v125
	v_mov_b32_e32 v109, v125
	v_mov_b32_e32 v108, v125
	v_mov_b32_e32 v107, v125
	v_mov_b32_e32 v106, v125
	v_mov_b32_e32 v97, v125
	v_mov_b32_e32 v96, v125
	v_mov_b32_e32 v95, v125
	v_mov_b32_e32 v94, v125
	v_mov_b32_e32 v93, v125
	v_mov_b32_e32 v92, v125
	v_mov_b32_e32 v91, v125
	v_mov_b32_e32 v90, v125
	v_mov_b32_e32 v81, v125
	v_mov_b32_e32 v80, v125
	v_mov_b32_e32 v79, v125
	v_mov_b32_e32 v78, v125
	v_mov_b32_e32 v77, v125
	v_mov_b32_e32 v76, v125
	v_mov_b32_e32 v75, v125
	v_mov_b32_e32 v74, v125
	v_mov_b32_e32 v121, v125
	v_mov_b32_e32 v120, v125
	v_mov_b32_e32 v119, v125
	v_mov_b32_e32 v118, v125
	v_mov_b32_e32 v117, v125
	v_mov_b32_e32 v116, v125
	v_mov_b32_e32 v115, v125
	v_mov_b32_e32 v114, v125
	v_mov_b32_e32 v105, v125
	v_mov_b32_e32 v104, v125
	v_mov_b32_e32 v103, v125
	v_mov_b32_e32 v102, v125
	v_mov_b32_e32 v101, v125
	v_mov_b32_e32 v100, v125
	v_mov_b32_e32 v99, v125
	v_mov_b32_e32 v98, v125
	v_mov_b32_e32 v89, v125
	v_mov_b32_e32 v88, v125
	v_mov_b32_e32 v87, v125
	v_mov_b32_e32 v86, v125
	v_mov_b32_e32 v85, v125
	v_mov_b32_e32 v84, v125
	v_mov_b32_e32 v83, v125
	v_mov_b32_e32 v82, v125
	v_mov_b32_e32 v73, v125
	v_mov_b32_e32 v72, v125
	v_mov_b32_e32 v71, v125
	v_mov_b32_e32 v70, v125
	v_mov_b32_e32 v69, v125
	v_mov_b32_e32 v68, v125
	v_mov_b32_e32 v67, v125
	v_mov_b32_e32 v66, v125
	v_mov_b32_e32 v65, v125
	v_mov_b32_e32 v64, v125
	v_mov_b32_e32 v63, v125
	v_mov_b32_e32 v62, v125
	v_mov_b32_e32 v61, v125
	v_mov_b32_e32 v60, v125
	v_mov_b32_e32 v59, v125
	v_mov_b32_e32 v58, v125
	v_mov_b32_e32 v49, v125
	v_mov_b32_e32 v48, v125
	v_mov_b32_e32 v47, v125
	v_mov_b32_e32 v46, v125
	v_mov_b32_e32 v45, v125
	v_mov_b32_e32 v44, v125
	v_mov_b32_e32 v43, v125
	v_mov_b32_e32 v42, v125
	v_mov_b32_e32 v33, v125
	v_mov_b32_e32 v32, v125
	v_mov_b32_e32 v31, v125
	v_mov_b32_e32 v30, v125
	v_mov_b32_e32 v29, v125
	v_mov_b32_e32 v28, v125
	v_mov_b32_e32 v27, v125
	v_mov_b32_e32 v26, v125
	v_mov_b32_e32 v17, v125
	v_mov_b32_e32 v16, v125
	v_mov_b32_e32 v15, v125
	v_mov_b32_e32 v14, v125
	v_mov_b32_e32 v13, v125
	v_mov_b32_e32 v12, v125
	v_mov_b32_e32 v11, v125
	v_mov_b32_e32 v10, v125
	v_mov_b32_e32 v57, v125
	v_mov_b32_e32 v56, v125
	v_mov_b32_e32 v55, v125
	v_mov_b32_e32 v54, v125
	v_mov_b32_e32 v53, v125
	v_mov_b32_e32 v52, v125
	v_mov_b32_e32 v51, v125
	v_mov_b32_e32 v50, v125
	v_mov_b32_e32 v41, v125
	v_mov_b32_e32 v40, v125
	v_mov_b32_e32 v39, v125
	v_mov_b32_e32 v38, v125
	v_mov_b32_e32 v37, v125
	v_mov_b32_e32 v36, v125
	v_mov_b32_e32 v35, v125
	v_mov_b32_e32 v34, v125
	v_mov_b32_e32 v25, v125
	v_mov_b32_e32 v24, v125
	v_mov_b32_e32 v23, v125
	v_mov_b32_e32 v22, v125
	v_mov_b32_e32 v21, v125
	v_mov_b32_e32 v20, v125
	v_mov_b32_e32 v19, v125
	v_mov_b32_e32 v18, v125
	v_mov_b32_e32 v9, v125
	v_mov_b32_e32 v8, v125
	v_mov_b32_e32 v7, v125
	v_mov_b32_e32 v6, v125
	v_mov_b32_e32 v5, v125
	v_mov_b32_e32 v4, v125
	v_mov_b32_e32 v3, v125
	v_mov_b32_e32 v2, v125
	s_cbranch_vccnz .LBB0_958
	s_add_u32 s36, s36, 0x80
	s_addc_u32 s37, s37, 0
	s_add_u32 s50, s40, 0x100
	s_addc_u32 s51, s41, 0
	s_mov_b32 s40, 0
	v_mov_b64_e32 v[2:3], 0
	v_mov_b64_e32 v[4:5], 0
	v_mov_b64_e32 v[6:7], 0
	v_mov_b64_e32 v[8:9], 0
	v_mov_b64_e32 v[10:11], 0
	v_mov_b64_e32 v[12:13], 0
	v_mov_b64_e32 v[14:15], 0
	v_mov_b64_e32 v[16:17], 0
	v_mov_b64_e32 v[18:19], 0
	v_mov_b64_e32 v[20:21], 0
	v_mov_b64_e32 v[22:23], 0
	v_mov_b64_e32 v[24:25], 0
	v_mov_b64_e32 v[26:27], 0
	v_mov_b64_e32 v[28:29], 0
	v_mov_b64_e32 v[30:31], 0
	v_mov_b64_e32 v[32:33], 0
	v_mov_b64_e32 v[34:35], 0
	v_mov_b64_e32 v[36:37], 0
	v_mov_b64_e32 v[38:39], 0
	v_mov_b64_e32 v[40:41], 0
	v_mov_b64_e32 v[42:43], 0
	v_mov_b64_e32 v[44:45], 0
	v_mov_b64_e32 v[46:47], 0
	v_mov_b64_e32 v[48:49], 0
	v_mov_b64_e32 v[50:51], 0
	v_mov_b64_e32 v[52:53], 0
	v_mov_b64_e32 v[54:55], 0
	v_mov_b64_e32 v[56:57], 0
	v_mov_b64_e32 v[58:59], 0
	v_mov_b64_e32 v[60:61], 0
	v_mov_b64_e32 v[62:63], 0
	v_mov_b64_e32 v[64:65], 0
	v_mov_b64_e32 v[66:67], 0
	v_mov_b64_e32 v[68:69], 0
	v_mov_b64_e32 v[70:71], 0
	v_mov_b64_e32 v[72:73], 0
	v_mov_b64_e32 v[74:75], 0
	v_mov_b64_e32 v[76:77], 0
	v_mov_b64_e32 v[78:79], 0
	v_mov_b64_e32 v[80:81], 0
	v_mov_b64_e32 v[82:83], 0
	v_mov_b64_e32 v[84:85], 0
	v_mov_b64_e32 v[86:87], 0
	v_mov_b64_e32 v[88:89], 0
	v_mov_b64_e32 v[90:91], 0
	v_mov_b64_e32 v[92:93], 0
	v_mov_b64_e32 v[94:95], 0
	v_mov_b64_e32 v[96:97], 0
	v_mov_b64_e32 v[98:99], 0
	v_mov_b64_e32 v[100:101], 0
	v_mov_b64_e32 v[102:103], 0
	v_mov_b64_e32 v[104:105], 0
	v_mov_b64_e32 v[106:107], 0
	v_mov_b64_e32 v[108:109], 0
	v_mov_b64_e32 v[110:111], 0
	v_mov_b64_e32 v[112:113], 0
	v_mov_b64_e32 v[114:115], 0
	v_mov_b64_e32 v[116:117], 0
	v_mov_b64_e32 v[118:119], 0
	v_mov_b64_e32 v[120:121], 0
	v_mov_b64_e32 v[122:123], 0
	v_mov_b64_e32 v[124:125], 0
	v_mov_b64_e32 v[126:127], 0
	v_mov_b64_e32 v[128:129], 0
	.p2align 6

.LBB0_985:
	s_ashr_i32 s21, s20, 31
	s_lshl_b64 s[18:19], s[20:21], 19
	s_add_u32 s34, s29, s18
	s_addc_u32 s35, s44, s19
	s_and_b64 s[18:19], s[40:41], exec
	s_cselect_b32 s3, s35, s13
	s_cselect_b32 s16, s34, s12
	s_ashr_i32 s15, s14, 31
	s_lshl_b64 s[18:19], s[14:15], 19
	s_add_u32 s42, s45, s18
	s_addc_u32 s43, s46, s19
	s_and_b64 s[18:19], s[40:41], exec
	s_cselect_b32 s15, s43, s31
	s_cselect_b32 s18, s42, s30
	s_add_u32 s12, s12, 0x40080
	s_addc_u32 s13, s13, 0
	s_add_u32 s19, s30, 0x100
	s_addc_u32 s21, s31, 0
	s_mov_b32 s24, -2
	v_mov_b64_e32 v[2:3], 0
	v_mov_b64_e32 v[4:5], 0
	v_mov_b64_e32 v[6:7], 0
	v_mov_b64_e32 v[8:9], 0
	v_mov_b64_e32 v[10:11], 0
	v_mov_b64_e32 v[12:13], 0
	v_mov_b64_e32 v[14:15], 0
	v_mov_b64_e32 v[16:17], 0
	v_mov_b64_e32 v[18:19], 0
	v_mov_b64_e32 v[20:21], 0
	v_mov_b64_e32 v[22:23], 0
	v_mov_b64_e32 v[24:25], 0
	v_mov_b64_e32 v[26:27], 0
	v_mov_b64_e32 v[28:29], 0
	v_mov_b64_e32 v[30:31], 0
	v_mov_b64_e32 v[32:33], 0
	v_mov_b64_e32 v[34:35], 0
	v_mov_b64_e32 v[36:37], 0
	v_mov_b64_e32 v[38:39], 0
	v_mov_b64_e32 v[40:41], 0
	v_mov_b64_e32 v[42:43], 0
	v_mov_b64_e32 v[44:45], 0
	v_mov_b64_e32 v[46:47], 0
	v_mov_b64_e32 v[48:49], 0
	v_mov_b64_e32 v[50:51], 0
	v_mov_b64_e32 v[52:53], 0
	v_mov_b64_e32 v[54:55], 0
	v_mov_b64_e32 v[56:57], 0
	v_mov_b64_e32 v[58:59], 0
	v_mov_b64_e32 v[60:61], 0
	v_mov_b64_e32 v[62:63], 0
	v_mov_b64_e32 v[64:65], 0
	v_mov_b64_e32 v[66:67], 0
	v_mov_b64_e32 v[68:69], 0
	v_mov_b64_e32 v[70:71], 0
	v_mov_b64_e32 v[72:73], 0
	v_mov_b64_e32 v[74:75], 0
	v_mov_b64_e32 v[76:77], 0
	v_mov_b64_e32 v[78:79], 0
	v_mov_b64_e32 v[80:81], 0
	v_mov_b64_e32 v[82:83], 0
	v_mov_b64_e32 v[84:85], 0
	v_mov_b64_e32 v[86:87], 0
	v_mov_b64_e32 v[88:89], 0
	v_mov_b64_e32 v[90:91], 0
	v_mov_b64_e32 v[92:93], 0
	v_mov_b64_e32 v[94:95], 0
	v_mov_b64_e32 v[96:97], 0
	v_mov_b64_e32 v[98:99], 0
	v_mov_b64_e32 v[100:101], 0
	v_mov_b64_e32 v[102:103], 0
	v_mov_b64_e32 v[104:105], 0
	v_mov_b64_e32 v[106:107], 0
	v_mov_b64_e32 v[108:109], 0
	v_mov_b64_e32 v[110:111], 0
	v_mov_b64_e32 v[112:113], 0
	v_mov_b64_e32 v[114:115], 0
	v_mov_b64_e32 v[116:117], 0
	v_mov_b64_e32 v[118:119], 0
	v_mov_b64_e32 v[120:121], 0
	v_mov_b64_e32 v[122:123], 0
	v_mov_b64_e32 v[124:125], 0
	v_mov_b64_e32 v[126:127], 0
	v_mov_b64_e32 v[128:129], 0
	.p2align 6
